# comb10 + final-norm epilogue: coherent partial re-read with 10 loads instead of 16 (pairs widened to 16 bytes)
# speedup vs baseline: 1.0044x; 1.0011x over previous
;     __device__ __forceinline__ void operator()(f32x4 (&acc)[2][2][4][2], const Unit& u, int wr, int wc, int fr, int fq) const {
;     ...
;             while ((unsigned)__builtin_amdgcn_readfirstlane(__hip_atomic_load(c, __ATOMIC_RELAXED, __HIP_MEMORY_SCOPE_AGENT)) < 64u) { __builtin_amdgcn_s_sleep(4); if (++sp > (1u << 21)) break; }
;             __builtin_amdgcn_fence(__ATOMIC_ACQUIRE, "agent");
;             const unsigned long long* p = (const unsigned long long*)(part + (size_t)(u.pm * BM + threadIdx.x) * NPART); float s = 0.f;
; #pragma unroll
;             for (int j = 0; j < 16; ++j) { const unsigned long long w = __hip_atomic_load(p + j, __ATOMIC_RELAXED, __HIP_MEMORY_SCOPE_AGENT); s += __uint_as_float((unsigned)w) + __uint_as_float((unsigned)(w >> 32)); }
;             R[threadIdx.x] = rsqrtf(s * (1.0f / D) + RMS_EPS);
.LBB0_1313:
	v_or_b32_e32 v136, s39, v221
	s_waitcnt lgkmcnt(0)
	v_lshlrev_b64 v[0:1], 7, v[136:137]
	v_lshl_add_u64 v[0:1], s[48:49], 0, v[0:1]
	buffer_inv sc1
	global_load_dwordx4 v[2:5], v[0:1], off sc1
	global_load_dwordx2 v[6:7], v[0:1], off offset:16 sc1
	global_load_dwordx2 v[158:159], v[0:1], off offset:24 sc1
	global_load_dwordx4 v[192:195], v[0:1], off offset:32 sc1
	global_load_dwordx4 v[196:199], v[0:1], off offset:48 sc1
	global_load_dwordx4 v[200:203], v[0:1], off offset:64 sc1
	global_load_dwordx4 v[204:207], v[0:1], off offset:80 sc1
	global_load_dwordx4 v[208:211], v[0:1], off offset:96 sc1
	global_load_dwordx2 v[212:213], v[0:1], off offset:112 sc1
	s_nop 0
	global_load_dwordx2 v[0:1], v[0:1], off offset:120 sc1
	s_waitcnt vmcnt(9)
	v_add_f32_e32 v2, v2, v3
	s_waitcnt vmcnt(9)
	v_add_f32_e32 v3, v4, v5
	s_waitcnt vmcnt(8)
	v_add_f32_e32 v4, v6, v7
	s_waitcnt vmcnt(7)
	v_add_f32_e32 v5, v158, v159
	s_waitcnt vmcnt(6)
	v_add_f32_e32 v6, v192, v193
	s_waitcnt vmcnt(6)
	v_add_f32_e32 v7, v194, v195
	s_waitcnt vmcnt(5)
	v_add_f32_e32 v136, v196, v197
	s_waitcnt vmcnt(5)
	v_add_f32_e32 v158, v198, v199
	s_waitcnt vmcnt(4)
	v_add_f32_e32 v159, v200, v201
	s_waitcnt vmcnt(4)
	v_add_f32_e32 v160, v202, v203
	s_waitcnt vmcnt(3)
	v_add_f32_e32 v162, v204, v205
	s_waitcnt vmcnt(3)
	v_add_f32_e32 v164, v206, v207
	s_waitcnt vmcnt(2)
	v_add_f32_e32 v166, v208, v209
	s_waitcnt vmcnt(2)
	v_add_f32_e32 v168, v210, v211
	s_waitcnt vmcnt(1)
	v_add_f32_e32 v170, v212, v213
	s_waitcnt vmcnt(0)
	v_add_f32_e32 v0, v0, v1
	v_add_f32_e32 v1, 0, v2
	v_add_f32_e32 v1, v1, v3
	v_add_f32_e32 v1, v1, v4
	v_add_f32_e32 v1, v1, v5
	v_add_f32_e32 v1, v1, v6
	v_add_f32_e32 v1, v1, v7
	v_add_f32_e32 v1, v1, v136
	v_add_f32_e32 v1, v1, v158
	v_add_f32_e32 v1, v1, v159
	v_add_f32_e32 v1, v1, v160
	v_add_f32_e32 v1, v1, v162
	v_add_f32_e32 v1, v1, v164
	v_add_f32_e32 v1, v1, v166
	v_add_f32_e32 v1, v1, v168
	v_add_f32_e32 v1, v1, v170
	v_add_f32_e32 v0, v1, v0
	v_fmamk_f32 v0, v0, 0x3a000000, v190
	v_mul_f32_e32 v1, 0x4b800000, v0
	v_cmp_gt_f32_e32 vcc, s73, v0
	s_nop 1
	v_cndmask_b32_e32 v0, v0, v1, vcc
	v_rsq_f32_e32 v0, v0
	s_nop 0
	v_mul_f32_e32 v1, 0x45800000, v0
	v_cndmask_b32_e32 v0, v0, v1, vcc
	ds_write_b32 v177, v0
